# prologue de-serialisation: in the MLA attention item start the second K/V tile's global loads are issued before waiting on the first tile (first-tile LDS staging writes sunk below them, counted waits
# baseline (speedup 1.0000x reference)
; DI int otid() { int t = threadIdx.x; asm volatile("" : "+v"(t)); return t; }
; template <int DQK, int NMAP, int DV> ...
;     ...
;   const int tid = otid(), lane = tid & 63, w = __builtin_amdgcn_readfirstlane(tid >> 6), l32 = lane & 31, g = lane >> 5;
;   bf16x8 qf[NMAP][NKS];
;   {
;     const bf16_t* qrow = q + (size_t)(q0 + 32 * w + l32) * qs + 8 * g;
; #pragma unroll
;     for (int c = 0; c < NMAP; ++c)
; #pragma unroll
;       for (int ks = 0; ks < NKS; ++ks) qf[c][ks] = *(const bf16x8*)(qrow + c * DQK + 16 * ks);
;   }
;   float m[NMAP];
; #pragma unroll
;   for (int c = 0; c < NMAP; ++c) {
;     m[c] = m_init; lsum[c] = g == 0 ? l_init : 0.f;
; #pragma unroll
;     for (int db = 0; db < NDB; ++db)
; #pragma unroll
;       for (int r = 0; r < 16; ++r) O[c][db][r] = 0.f;
;   }
;   u32x4 rk[NKC], rv[NVC];
.LBB0_1365:
	s_bitcmp0_b32 s57, 0
	s_cselect_b32 s1, s84, s27
	s_add_i32 s0, s1, s0
	s_cmpk_gt_i32 s0, 0x1ff
	s_cbranch_scc1 .LBB0_1364
	s_ashr_i32 s59, s0, 5
	s_bfe_u32 s64, s0, 0x20003
	s_sub_i32 s62, 15, s59
	s_and_b32 s65, s0, 7
	s_mul_i32 s0, s64, 0xc00000
	s_add_u32 s0, s24, s0
	s_addc_u32 s1, s25, 0
	s_mul_i32 s2, s65, 0x180
	s_add_u32 s6, s0, s2
	s_addc_u32 s7, s1, 0
	s_lshl_b32 s63, s64, 23
	s_add_u32 s0, s33, s63
	s_addc_u32 s1, s40, 0
	s_lshl_b32 s66, s65, 8
	s_add_u32 s0, s0, s66
	v_mov_b32_e32 v200, v206
	s_addc_u32 s1, s1, 0
	s_lshl_b32 s61, s64, 19
	v_mov_b32_e32 v36, v206
	s_add_u32 s2, s41, s61
	s_addc_u32 s3, s44, 0
	v_readfirstlane_b32 s8, v36
	s_ashr_i32 s60, s8, 1
	s_lshl_b32 s30, s62, 8
	s_andn2_b32 s60, s60, 31
	v_and_b32_e32 v1, 31, v36
	s_add_i32 s58, s60, s30
	v_bfe_u32 v38, v36, 5, 1
	v_or_b32_e32 v201, s58, v1
	v_mov_b64_e32 v[2:3], s[6:7]
	v_mad_i64_i32 v[2:3], s[6:7], v201, s47, v[2:3]
	v_lshlrev_b32_e32 v4, 4, v38
	v_mov_b32_e32 v5, v0
	v_lshl_add_u64 v[2:3], v[2:3], 0, v[4:5]
	global_load_dwordx4 v[156:159], v[2:3], off
	global_load_dwordx4 v[152:155], v[2:3], off offset:32
	global_load_dwordx4 v[148:151], v[2:3], off offset:64
	global_load_dwordx4 v[144:147], v[2:3], off offset:96
	global_load_dwordx4 v[140:143], v[2:3], off offset:128
	global_load_dwordx4 v[136:139], v[2:3], off offset:160
	global_load_dwordx4 v[132:135], v[2:3], off offset:192
	global_load_dwordx4 v[128:131], v[2:3], off offset:224
	global_load_dwordx4 v[124:127], v[2:3], off offset:256
	global_load_dwordx4 v[120:123], v[2:3], off offset:288
	global_load_dwordx4 v[116:119], v[2:3], off offset:320
	global_load_dwordx4 v[112:115], v[2:3], off offset:352
	v_mul_hi_i32 v2, v36, s48
	v_lshrrev_b32_e32 v3, 31, v2
	v_ashrrev_i32_e32 v2, 2, v2
	v_add_u32_e32 v16, v2, v3
	v_mul_lo_u32 v2, v16, 24
	v_sub_u32_e32 v37, v36, v2
	v_ashrrev_i32_e32 v17, 31, v16
	v_lshlrev_b32_e32 v10, 3, v37
	v_cmp_gt_i32_e64 s[6:7], 16, v37
	v_cmp_lt_i32_e32 vcc, 15, v37
	v_lshlrev_b64 v[12:13], 7, v[16:17]
	s_and_saveexec_b64 s[8:9], vcc
	s_xor_b64 s[8:9], exec, s[8:9]
	v_lshl_add_u64 v[2:3], s[2:3], 0, v[12:13]
	v_mov_b32_e32 v11, v0
	v_lshl_add_u64 v[2:3], v[10:11], 1, v[2:3]
	v_lshl_add_u64 v[2:3], v[2:3], 0, s[34:35]
	s_or_saveexec_b64 s[8:9], s[8:9]
	v_lshlrev_b64 v[14:15], 11, v[16:17]
	v_ashrrev_i32_e32 v17, 31, v10
	s_xor_b64 exec, exec, s[8:9]
	v_lshl_add_u64 v[2:3], s[0:1], 0, v[14:15]
	v_mov_b32_e32 v11, v17
	v_lshl_add_u64 v[2:3], v[10:11], 1, v[2:3]
	s_or_b64 exec, exec, s[8:9]
	global_load_dwordx4 v[228:231], v[2:3], off
	v_add_u32_e32 v39, 0x200, v36
	v_mul_hi_i32 v6, v39, s48
	v_lshrrev_b32_e32 v7, 31, v6
	v_ashrrev_i32_e32 v6, 2, v6
	v_add_u32_e32 v24, v6, v7
	v_mul_lo_u32 v6, v24, 24
	v_sub_u32_e32 v11, v39, v6
	v_ashrrev_i32_e32 v25, 31, v24
	v_lshlrev_b32_e32 v18, 3, v11
	v_cmp_gt_i32_e64 s[8:9], 16, v11
	v_cmp_lt_i32_e64 s[12:13], 15, v11
	v_lshlrev_b64 v[20:21], 7, v[24:25]
	s_and_saveexec_b64 s[10:11], s[12:13]
	s_xor_b64 s[10:11], exec, s[10:11]
	v_lshl_add_u64 v[6:7], s[2:3], 0, v[20:21]
	v_mov_b32_e32 v19, v0
	v_lshl_add_u64 v[6:7], v[18:19], 1, v[6:7]
	v_lshl_add_u64 v[6:7], v[6:7], 0, s[34:35]
	s_or_saveexec_b64 s[10:11], s[10:11]
	v_lshlrev_b64 v[22:23], 11, v[24:25]
	v_ashrrev_i32_e32 v25, 31, v18
	s_xor_b64 exec, exec, s[10:11]
	v_lshl_add_u64 v[6:7], s[0:1], 0, v[22:23]
	v_mov_b32_e32 v19, v25
	v_lshl_add_u64 v[6:7], v[18:19], 1, v[6:7]
	s_or_b64 exec, exec, s[10:11]
	global_load_dwordx4 v[232:235], v[6:7], off
	v_add_u32_e32 v19, 0x400, v36
	v_mul_hi_i32 v26, v19, s48
	v_lshrrev_b32_e32 v27, 31, v26
	v_ashrrev_i32_e32 v26, 2, v26
	v_add_u32_e32 v34, v26, v27
	v_mul_lo_u32 v26, v34, 24
	v_sub_u32_e32 v19, v19, v26
	v_ashrrev_i32_e32 v35, 31, v34
	v_lshlrev_b32_e32 v26, 3, v19
	v_cmp_gt_i32_e64 s[10:11], 16, v19
	v_cmp_lt_i32_e64 s[14:15], 15, v19
	v_lshlrev_b64 v[28:29], 7, v[34:35]
	s_and_saveexec_b64 s[16:17], s[14:15]
	s_xor_b64 s[16:17], exec, s[16:17]
	v_lshl_add_u64 v[30:31], s[2:3], 0, v[28:29]
	v_mov_b32_e32 v27, v0
	v_lshl_add_u64 v[30:31], v[26:27], 1, v[30:31]
	v_lshl_add_u64 v[32:33], v[30:31], 0, s[34:35]
	s_or_saveexec_b64 s[16:17], s[16:17]
	v_lshlrev_b64 v[30:31], 11, v[34:35]
	v_ashrrev_i32_e32 v35, 31, v26
	s_xor_b64 exec, exec, s[16:17]
	v_lshl_add_u64 v[32:33], s[0:1], 0, v[30:31]
	v_mov_b32_e32 v27, v35
	v_lshl_add_u64 v[32:33], v[26:27], 1, v[32:33]
	s_or_b64 exec, exec, s[16:17]
	s_lshl_b32 s16, s65, 20
	s_or_b32 s16, s63, s16
	v_lshlrev_b32_e32 v27, 3, v36
	s_add_u32 s16, s45, s16
	v_and_b32_e32 v205, 56, v27
	v_ashrrev_i32_e32 v52, 3, v36
	v_ashrrev_i32_e32 v54, 3, v39
	s_addc_u32 s17, s46, 0
	global_load_dwordx4 v[40:43], v[32:33], off
	v_lshlrev_b32_e32 v32, 1, v205
	v_mov_b32_e32 v33, v0
	v_ashrrev_i32_e32 v53, 31, v52
	v_ashrrev_i32_e32 v55, 31, v54
	v_lshl_add_u64 v[180:181], s[16:17], 0, v[32:33]
	v_lshlrev_b64 v[182:183], 13, v[52:53]
	v_lshlrev_b64 v[184:185], 13, v[54:55]
	v_lshl_add_u64 v[44:45], v[180:181], 0, v[182:183]
	v_lshl_add_u64 v[48:49], v[180:181], 0, v[184:185]
	global_load_dwordx4 v[44:47], v[44:45], off
	s_nop 0
	global_load_dwordx4 v[48:51], v[48:49], off
	v_mul_lo_u32 v207, v16, s49
	v_lshlrev_b32_e32 v208, 4, v37
	v_mul_lo_u32 v209, v24, s49
	v_lshlrev_b32_e32 v210, 4, v11
	v_add3_u32 v236, 16, v207, v208
	v_mul_lo_u32 v211, v34, s49
	v_lshlrev_b32_e32 v212, 4, v19
	v_add_u32_e32 v36, 64, v16
; #define ATTN_LOAD(KT) { ATTN_LOAD_K(KT); ATTN_LOAD_V(KT); }
; #define ATTN_STORE(ST) { ATTN_STORE_K(ST); ATTN_STORE_V(ST); }
; template <int DQK, int NMAP, int DV> ...
;     ...
;   float m[NMAP];
; #pragma unroll
;   for (int c = 0; c < NMAP; ++c) {
;     m[c] = m_init; lsum[c] = g == 0 ? l_init : 0.f;
; #pragma unroll
;     for (int db = 0; db < NDB; ++db)
; #pragma unroll
;       for (int r = 0; r < 16; ++r) O[c][db][r] = 0.f;
;   }
;     ...
;   ATTN_LOAD(kt_lo);
;   ATTN_STORE(0);
;   if (kt_lo < kt_hi) ATTN_LOAD(kt_lo + 1);
;   const int qmin = q0 + 32 * w, qmax = qmin + 31, qpos = qmin + l32;
	v_add3_u32 v237, 16, v209, v210
	v_mul_lo_u32 v214, v52, s50
	v_mul_lo_u32 v215, v54, s50
	v_add_u32_e32 v2, 16, v32
	v_add3_u32 v238, 16, v211, v212
	v_add3_u32 v239, v2, v214, s51
	v_add3_u32 v240, v2, v215, s51
	v_ashrrev_i32_e32 v37, 31, v36
	s_and_saveexec_b64 s[18:19], vcc
	s_xor_b64 s[18:19], exec, s[18:19]
	v_lshlrev_b64 v[2:3], 7, v[36:37]
	v_lshl_add_u64 v[2:3], s[2:3], 0, v[2:3]
	v_mov_b32_e32 v11, v0
	v_lshl_add_u64 v[2:3], v[10:11], 1, v[2:3]
	v_lshl_add_u64 v[2:3], v[2:3], 0, s[34:35]
	s_andn2_saveexec_b64 s[18:19], s[18:19]
	v_lshlrev_b64 v[2:3], 11, v[36:37]
	v_lshl_add_u64 v[2:3], s[0:1], 0, v[2:3]
	v_mov_b32_e32 v11, v17
	v_lshl_add_u64 v[2:3], v[10:11], 1, v[2:3]
	s_or_b64 exec, exec, s[18:19]
	global_load_dwordx4 v[160:163], v[2:3], off
	v_add_u32_e32 v4, 64, v24
	v_ashrrev_i32_e32 v5, 31, v4
	s_and_saveexec_b64 s[18:19], s[12:13]
	s_xor_b64 s[12:13], exec, s[18:19]
	v_lshlrev_b64 v[2:3], 7, v[4:5]
	v_lshl_add_u64 v[2:3], s[2:3], 0, v[2:3]
	v_mov_b32_e32 v19, v0
	v_lshl_add_u64 v[2:3], v[18:19], 1, v[2:3]
	v_lshl_add_u64 v[2:3], v[2:3], 0, s[34:35]
	s_andn2_saveexec_b64 s[12:13], s[12:13]
	v_lshlrev_b64 v[2:3], 11, v[4:5]
	v_lshl_add_u64 v[2:3], s[0:1], 0, v[2:3]
	v_mov_b32_e32 v19, v25
	v_lshl_add_u64 v[2:3], v[18:19], 1, v[2:3]
	s_or_b64 exec, exec, s[12:13]
	global_load_dwordx4 v[164:167], v[2:3], off
	v_add_u32_e32 v6, 64, v34
	v_ashrrev_i32_e32 v7, 31, v6
	v_mov_b32_e32 v27, v0
	s_and_saveexec_b64 s[12:13], s[14:15]
	s_xor_b64 s[12:13], exec, s[12:13]
	v_lshlrev_b64 v[2:3], 7, v[6:7]
	v_lshl_add_u64 v[2:3], s[2:3], 0, v[2:3]
	v_lshl_add_u64 v[2:3], v[26:27], 1, v[2:3]
	v_lshl_add_u64 v[4:5], v[2:3], 0, s[34:35]
	s_or_saveexec_b64 s[2:3], s[12:13]
	v_mov_b64_e32 v[2:3], v[26:27]
	s_xor_b64 exec, exec, s[2:3]
	v_lshlrev_b64 v[2:3], 11, v[6:7]
	v_lshl_add_u64 v[2:3], s[0:1], 0, v[2:3]
	v_mov_b32_e32 v34, v26
	v_lshl_add_u64 v[4:5], v[34:35], 1, v[2:3]
	v_mov_b64_e32 v[2:3], v[34:35]
	s_or_b64 exec, exec, s[2:3]
	global_load_dwordx4 v[176:179], v[4:5], off
	v_lshl_add_u64 v[4:5], s[16:17], 0, v[182:183]
	v_mov_b32_e32 v33, v0
	v_lshl_add_u64 v[4:5], v[4:5], 0, v[32:33]
	v_lshl_add_u64 v[6:7], s[16:17], 0, v[184:185]
	v_lshl_add_u64 v[6:7], v[6:7], 0, v[32:33]
	global_load_dwordx4 v[168:171], v[4:5], off offset:128
	global_load_dwordx4 v[172:175], v[6:7], off offset:128
	s_waitcnt vmcnt(9)
	ds_write_b128 v236, v[228:231]
	s_waitcnt vmcnt(8)
	ds_write_b128 v237, v[232:235]
	s_waitcnt vmcnt(7)
	ds_write_b128 v238, v[40:43]
	s_waitcnt vmcnt(6)
	ds_write2_b64 v239, v[44:45], v[46:47] offset1:1
	s_waitcnt vmcnt(5)
	ds_write2_b64 v240, v[48:49], v[50:51] offset1:1
	s_lshl_b32 s0, s62, 2
	s_lshl_b32 s15, s64, 12
	s_lshl_b32 s14, s65, 7
	s_or_b32 s17, s0, 3
	s_or_b32 s16, s58, 31
	s_add_u32 s0, s63, s66
	s_addc_u32 s1, 0, 0
	s_add_u32 s0, s0, 0x18500000
	s_addc_u32 s1, s1, 0
	s_add_u32 s2, s61, 0x1a4c3f00
	v_lshl_add_u64 v[4:5], s[0:1], 0, v[30:31]
	s_addc_u32 s3, 0, 0
	v_lshl_add_u64 v[186:187], v[2:3], 1, v[4:5]
	v_lshl_add_u64 v[2:3], s[2:3], 0, v[28:29]
	v_mov_b32_e32 v24, v18
	v_lshl_add_u64 v[188:189], v[26:27], 1, v[2:3]
	v_lshl_add_u64 v[2:3], s[0:1], 0, v[22:23]
	v_mov_b32_e32 v19, v0
	v_lshl_add_u64 v[190:191], v[24:25], 1, v[2:3]
	v_lshl_add_u64 v[2:3], s[2:3], 0, v[20:21]
	s_addk_i32 s60, 0xf00
	v_mul_u32_u24_e32 v216, 0x190, v1
	v_mul_u32_u24_e32 v213, 0x88, v1
	v_lshlrev_b32_e32 v204, 2, v38
	v_mov_b32_e32 v16, v10
	v_lshl_add_u64 v[192:193], v[18:19], 1, v[2:3]
	v_lshl_add_u64 v[2:3], s[0:1], 0, v[14:15]
	s_lshl_b32 s0, s59, 2
	v_add_u32_e32 v1, s60, v1
	v_lshlrev_b32_e32 v32, 3, v38
	v_mov_b32_e32 v11, v0
	v_lshl_add_u64 v[194:195], v[16:17], 1, v[2:3]
	v_lshl_add_u64 v[2:3], s[2:3], 0, v[12:13]
	s_sub_i32 s18, 63, s0
	v_sub_u32_e32 v1, v1, v204
	s_lshl_b32 s0, s59, 8
	v_mov_b32_e32 v14, v0
	v_mov_b32_e32 v15, v0
	v_lshl_add_u64 v[196:197], v[10:11], 1, v[2:3]
	v_subrev_u32_e32 v217, s0, v1
	v_mov_b32_e32 v1, v0
	v_mov_b32_e32 v2, v0
	v_mov_b32_e32 v3, v0
	v_mov_b32_e32 v4, v0
	v_mov_b32_e32 v5, v0
	v_mov_b32_e32 v6, v0
	v_mov_b32_e32 v7, v0
	v_mov_b32_e32 v8, v0
	v_mov_b32_e32 v9, v0
	v_mov_b32_e32 v10, v0
	v_mov_b32_e32 v12, v0
	v_mov_b32_e32 v13, v0
	v_lshlrev_b32_e32 v218, 1, v32
	v_mov_b64_e32 v[30:31], v[14:15]
	v_mov_b64_e32 v[46:47], v[14:15]
	v_mov_b64_e32 v[62:63], v[14:15]
	v_mov_b64_e32 v[78:79], v[14:15]
	s_mov_b32 s19, 0
	v_mov_b32_e32 v202, 0xf149f2ca
	v_mov_b32_e32 v203, 0
	v_mov_b64_e32 v[28:29], v[12:13]
	v_mov_b64_e32 v[26:27], v[10:11]
	v_mov_b64_e32 v[24:25], v[8:9]
	v_mov_b64_e32 v[22:23], v[6:7]
	v_mov_b64_e32 v[20:21], v[4:5]
	v_mov_b64_e32 v[18:19], v[2:3]
	v_mov_b64_e32 v[16:17], v[0:1]
	v_mov_b64_e32 v[44:45], v[12:13]
	v_mov_b64_e32 v[42:43], v[10:11]
	v_mov_b64_e32 v[40:41], v[8:9]
	v_mov_b64_e32 v[38:39], v[6:7]
	v_mov_b64_e32 v[36:37], v[4:5]
	v_mov_b64_e32 v[34:35], v[2:3]
	v_mov_b64_e32 v[32:33], v[0:1]
	v_mov_b64_e32 v[60:61], v[12:13]
	v_mov_b64_e32 v[58:59], v[10:11]
	v_mov_b64_e32 v[56:57], v[8:9]
	v_mov_b64_e32 v[54:55], v[6:7]
	v_mov_b64_e32 v[52:53], v[4:5]
	v_mov_b64_e32 v[50:51], v[2:3]
	v_mov_b64_e32 v[48:49], v[0:1]
	v_mov_b64_e32 v[76:77], v[12:13]
	v_mov_b64_e32 v[74:75], v[10:11]
	v_mov_b64_e32 v[72:73], v[8:9]
	v_mov_b64_e32 v[70:71], v[6:7]
	v_mov_b64_e32 v[68:69], v[4:5]
	v_mov_b64_e32 v[66:67], v[2:3]
	v_mov_b64_e32 v[64:65], v[0:1]
	s_mov_b32 s59, 0
	s_branch .LBB0_1393
